# finalize phase: loads of both token tiles of a chunk issued together (second tile lands in the dead fragment registers), LN gain/bias read from LDS per use, dwordx4 accesses via permlane32_swap
# speedup vs baseline: 1.0602x; 1.0026x over previous
; #define LAS __attribute__((address_space(3)))
; DI void chunk_decode(int g, int& seq, int& c) { if (g < NCP) { seq = 0; c = g; } else { seq = 1 + (g - NCP) / NCS; c = (g - NCP) % NCS; } }
; DI void chunk_range(int c, int& t0, int& t1) { if (c == 0) { t0 = 0; t1 = 16; } else { t0 = 16 + 128 * (c - 1); t1 = t0 + 128; } }
; DI void phase_finalize(int wv, const Params& p, int l, LAS unsigned char* lds) {
;     unsigned char* ob = (unsigned char*)p.out;
;     const bf16_t* YL = (const bf16_t*)(ob + O_YL); const bf16_t* ZZ = (const bf16_t*)(p.ws + R_Z); const bf16_t* UU = (const bf16_t*)(ob + O_U);
;     const float* BON = (const float*)(ob + O_BON);
;     const bf16_t* VV = (const bf16_t*)(p.ws + R_VV); const bf16_t* G = (const bf16_t*)(p.ws + R_G); bf16_t* MIX = (bf16_t*)(p.ws + R_MIX);
;     const int tid = tid_(wv), lane = tid & 63, w = tid >> 6, hd = w >> 1, half = w & 1;
;     LAS float* Ssm = (LAS float*)lds;
;     const float* lng = p.in[19] + (size_t)l * 256 + hd * 64; const float* lnb = p.in[20] + (size_t)l * 256 + hd * 64;
;     for (int g = blockIdx.x; g < NCH; g += gridDim.x) {
;         int seq, c; chunk_decode(g, seq, c); int t0, t1; chunk_range(c, t0, t1);
;         const int t = t0 + 64 * half + lane; const bool valid = t < t1; const size_t row = (size_t)seq_start(seq) + (valid ? t : t0);
;     ...
;                 const f32x4 g0 = *(const f32x4*)(lng + 8 * q), g1 = *(const f32x4*)(lng + 8 * q + 4), b0 = *(const f32x4*)(lnb + 8 * q), b1 = *(const f32x4*)(lnb + 8 * q + 4);
.LBB0_1298:
	s_or_b64 exec, exec, s[6:7]
	s_cmpk_lt_i32 s2, 0x2a1
	s_waitcnt lgkmcnt(0)
	v_mov_b32_e32 v0, v254
	s_cselect_b64 s[36:37], -1, 0
	s_cmpk_gt_i32 s2, 0x2a0
	s_barrier
	v_writelane_b32 v255, s4, 17
	v_writelane_b32 v255, s5, 18
	v_writelane_b32 v255, s6, 19
	v_writelane_b32 v255, s7, 20
	v_writelane_b32 v255, s8, 21
	v_writelane_b32 v255, s9, 22
	v_writelane_b32 v255, s10, 23
	v_writelane_b32 v255, s11, 24
	v_writelane_b32 v255, s12, 25
	v_writelane_b32 v255, s13, 26
	v_writelane_b32 v255, s14, 27
	v_writelane_b32 v255, s15, 28
	v_writelane_b32 v255, s16, 29
	v_writelane_b32 v255, s17, 30
	v_writelane_b32 v255, s18, 31
	v_writelane_b32 v255, s19, 32
	v_writelane_b32 v255, s20, 33
	v_writelane_b32 v255, s21, 34
	v_writelane_b32 v255, s22, 35
	v_writelane_b32 v255, s23, 36
	v_writelane_b32 v255, s24, 37
	v_writelane_b32 v255, s25, 38
	v_writelane_b32 v255, s26, 39
	v_writelane_b32 v255, s27, 40
	v_writelane_b32 v255, s28, 41
	v_writelane_b32 v255, s29, 42
	v_writelane_b32 v255, s30, 43
	v_writelane_b32 v255, s31, 44
	v_writelane_b32 v255, s36, 45
	v_writelane_b32 v255, s37, 46
	v_writelane_b32 v255, s38, 47
	v_writelane_b32 v255, s39, 48
	v_writelane_b32 v255, s40, 49
	v_writelane_b32 v255, s41, 50
	v_writelane_b32 v255, s42, 51
	v_writelane_b32 v255, s43, 52
	v_writelane_b32 v255, s44, 53
	v_writelane_b32 v255, s45, 54
	v_writelane_b32 v255, s46, 55
	v_writelane_b32 v255, s47, 56
	v_writelane_b32 v255, s48, 57
	v_writelane_b32 v255, s49, 58
	v_writelane_b32 v255, s50, 59
	v_writelane_b32 v255, s51, 60
	s_load_dwordx2 s[40:41], s[0:1], 0x120
	s_load_dwordx4 s[24:27], s[0:1], 0x98
	s_lshr_b32 s29, s33, 7
	s_bfe_u32 s30, s33, 0x10006
	s_lshl_b32 s31, s29, 7
	v_and_b32_e32 v1, 31, v254
	v_lshrrev_b32_e32 v2, 5, v254
	v_lshlrev_b32_e32 v13, 4, v2
	v_lshlrev_b32_e32 v14, 3, v2
	v_lshl_add_u32 v3, v1, 7, v13
	v_add_u32_e32 v4, 0x1000, v3
	v_add_u32_e32 v6, 32, v1
	v_xor_b32_e32 v15, 32, v254
	v_lshlrev_b32_e32 v15, 2, v15
	s_waitcnt lgkmcnt(0)
	s_add_u32 s8, s34, 0x3a228000
	s_addc_u32 s9, s35, 0
	s_add_u32 s8, s8, s31
	s_addc_u32 s9, s9, 0
	s_add_u32 s10, s8, 0x2860000
	s_addc_u32 s11, s9, 0
	s_add_u32 s12, s40, 0x64f0000
	s_addc_u32 s13, s41, 0
	s_add_u32 s12, s12, s31
	s_addc_u32 s13, s13, 0
	s_add_u32 s14, s12, 0x2860000
	s_addc_u32 s15, s13, 0
	s_add_u32 s16, s34, 0x379c8000
	s_addc_u32 s17, s35, 0
	s_add_u32 s16, s16, s31
	s_addc_u32 s17, s17, 0
	s_add_u32 s18, s34, 0x236c8000
	s_addc_u32 s19, s35, 0
	s_add_u32 s18, s18, s31
	s_addc_u32 s19, s19, 0
	s_add_u32 s20, s34, 0x19548000
	s_addc_u32 s21, s35, 0
	s_add_u32 s20, s20, s31
	s_addc_u32 s21, s21, 0
	s_add_u32 s22, s40, 0x10b13000
	s_addc_u32 s23, s41, 0
	s_lshl_b32 s42, s29, 2
	s_add_u32 s22, s22, s42
	s_addc_u32 s23, s23, 0
	s_lshl_b32 s42, s29, 8
	s_add_u32 s24, s24, s42
	s_addc_u32 s25, s25, 0
	s_add_u32 s26, s26, s42
	s_addc_u32 s27, s27, 0
	s_add_u32 s48, s40, 0xb5b0000
	s_addc_u32 s49, s41, 0
	v_lshlrev_b32_e32 v232, 4, v254
	v_min_u32_e32 v232, 0xf0, v232
	global_load_dwordx4 v[144:147], v232, s[24:25]
	global_load_dwordx4 v[148:151], v232, s[26:27]
	s_lshl_b32 s42, s33, 4
	v_lshlrev_b32_e32 v233, 4, v254
	v_add_u32_e32 v233, s42, v233
	s_waitcnt vmcnt(0)
	s_mov_b64 s[50:51], exec
	s_mov_b64 exec, 0xffff
	ds_write_b128 v233, v[144:147]
	ds_write_b128 v233, v[148:151] offset:256
	s_mov_b64 exec, s[50:51]
	v_add_u32_e32 v232, s42, v13
	s_waitcnt lgkmcnt(0)
	s_mov_b32 s28, s2

; DI void phase_finalize(int wv, const Params& p, int l, LAS unsigned char* lds) {
;     ...
;         int seq, c; chunk_decode(g, seq, c); int t0, t1; chunk_range(c, t0, t1);
;         const int t = t0 + 64 * half + lane; const bool valid = t < t1; const size_t row = (size_t)seq_start(seq) + (valid ? t : t0);
;         float y[64];
; #pragma unroll
;         for (int i = 0; i < 64; ++i) y[i] = 0.f;
;         for (int dir = 0; dir < 2; ++dir) {
;             __syncthreads();
;             {
;                 const int h2 = tid >> 7, e0 = (tid & 127) * 32;
;                 const bf16_t* src = UU + ((((size_t)g * 4 + h2) * 2 + dir) * 4096) + e0;
; #pragma unroll
;                 for (int q = 0; q < 4; ++q) { const u32x4 v = *(const u32x4*)(src + 8 * q);
; #pragma unroll
;                     for (int e = 0; e < 4; ++e) { Ssm[h2 * 4096 + e0 + 8 * q + 2 * e] = lo_bf(v[e]); Ssm[h2 * 4096 + e0 + 8 * q + 2 * e + 1] = hi_bf(v[e]); } }
;             }
;             __syncthreads();
;             const size_t o = ((size_t)dir * MPAD + row) * 256 + hd * 64;
;             f32x2 z[32];
;             u32x4 zr[8], yr[8];
; #pragma unroll
;             for (int q = 0; q < 8; ++q) { zr[q] = *(const u32x4*)(ZZ + o + 8 * q); yr[q] = *(const u32x4*)(YL + o + 8 * q); }
;             __builtin_amdgcn_sched_barrier(0);
; #pragma unroll
;             for (int q = 0; q < 8; ++q) { const u32x4 zv = zr[q], yv = yr[q];
; #pragma unroll
;                 for (int e = 0; e < 4; ++e) { z[4 * q + e] = (f32x2){lo_bf(zv[e]), hi_bf(zv[e])}; y[8 * q + 2 * e] += lo_bf(yv[e]); y[8 * q + 2 * e + 1] += hi_bf(yv[e]); } }
;             const LAS float* Sh = Ssm + hd * 4096;
; #pragma unroll
;             for (int i = 0; i < 64; ++i) {
;                 f32x2 a0 = {0.f, 0.f}, a1 = {0.f, 0.f};
; #pragma unroll
;                 for (int j = 0; j < 16; ++j) { const f32x4 s4 = *(const LAS f32x4*)(Sh + i * 64 + 4 * j);
;                     a0 = __builtin_elementwise_fma((f32x2){s4[0], s4[1]}, z[2 * j], a0); a1 = __builtin_elementwise_fma((f32x2){s4[2], s4[3]}, z[2 * j + 1], a1); }
;                 y[i] += (a0[0] + a0[1]) + (a1[0] + a1[1]);
;     ...
;             const float bon = BON[row * 4 + hd];
;             u32x4 vr[8], gr[8];
; #pragma unroll
;             for (int q = 0; q < 8; ++q) { vr[q] = *(const u32x4*)(VV + row * 256 + hd * 64 + 8 * q); gr[q] = *(const u32x4*)(G + row * 256 + hd * 64 + 8 * q); }
.Lfina_dec:
	s_lshl_b32 s45, s42, 7
	s_sub_u32 s45, s45, 0x70
	s_cmp_eq_u32 s42, 0
	s_cselect_b32 s45, 0, s45
	s_cselect_b32 s46, 16, 0x80
	s_lshl_b32 s47, s30, 6
	s_add_u32 s43, s43, s45
	s_add_u32 s43, s43, s47
	s_sub_i32 s46, s46, s47
	s_cmp_lt_i32 s46, 1
	s_cbranch_scc1 .Lfina_next
	s_lshl_b32 s45, s28, 2
	s_add_u32 s45, s45, s29
	s_lshl_b32 s45, s45, 14
	s_add_u32 s4, s48, s45
	s_addc_u32 s5, s49, 0
	s_add_u32 s6, s4, 0x2000
	s_addc_u32 s7, s5, 0
	v_cmp_gt_i32_e64 s[36:37], s46, v1
	v_cmp_gt_i32_e64 s[38:39], s46, v6
	s_nop 1
	v_cndmask_b32_e64 v7, 0, v1, s[36:37]
	v_cndmask_b32_e64 v8, 0, v6, s[38:39]
	v_add_u32_e32 v7, s43, v7
	v_add_u32_e32 v8, s43, v8
	v_lshl_add_u32 v5, v7, 9, v13
	v_lshl_add_u32 v9, v8, 9, v13
	v_lshl_add_u32 v10, v7, 9, v14
	v_lshl_add_u32 v11, v8, 9, v14
	v_lshl_add_u32 v12, v7, 11, v13
	v_lshl_add_u32 v0, v8, 11, v13
	v_lshlrev_b32_e32 v7, 4, v7
	v_lshlrev_b32_e32 v8, 4, v8
	global_load_dwordx4 v[80:83], v3, s[4:5] offset:0
	global_load_dwordx4 v[84:87], v3, s[4:5] offset:32
	global_load_dwordx4 v[88:91], v3, s[4:5] offset:64
	global_load_dwordx4 v[92:95], v3, s[4:5] offset:96
	global_load_dwordx4 v[96:99], v4, s[4:5] offset:0
	global_load_dwordx4 v[100:103], v4, s[4:5] offset:32
	global_load_dwordx4 v[104:107], v4, s[4:5] offset:64
	global_load_dwordx4 v[108:111], v4, s[4:5] offset:96
	global_load_dwordx4 v[112:115], v5, s[8:9] offset:0
	global_load_dwordx4 v[116:119], v5, s[8:9] offset:32
	global_load_dwordx4 v[120:123], v5, s[8:9] offset:64
	global_load_dwordx4 v[124:127], v5, s[8:9] offset:96
	global_load_dwordx4 v[128:131], v9, s[8:9] offset:0
	global_load_dwordx4 v[132:135], v9, s[8:9] offset:32
	global_load_dwordx4 v[136:139], v9, s[8:9] offset:64
	global_load_dwordx4 v[140:143], v9, s[8:9] offset:96
	global_load_dwordx4 v[144:147], v3, s[6:7] offset:0
	global_load_dwordx4 v[148:151], v3, s[6:7] offset:32
	global_load_dwordx4 v[152:155], v3, s[6:7] offset:64
	global_load_dwordx4 v[156:159], v3, s[6:7] offset:96
	global_load_dwordx4 v[160:163], v4, s[6:7] offset:0
	global_load_dwordx4 v[164:167], v4, s[6:7] offset:32
	global_load_dwordx4 v[168:171], v4, s[6:7] offset:64
	global_load_dwordx4 v[172:175], v4, s[6:7] offset:96
	global_load_dwordx4 v[176:179], v5, s[10:11] offset:0
	global_load_dwordx4 v[180:183], v5, s[10:11] offset:32
	global_load_dwordx4 v[184:187], v5, s[10:11] offset:64
	global_load_dwordx4 v[188:191], v5, s[10:11] offset:96
	global_load_dwordx4 v[192:195], v9, s[10:11] offset:0
	global_load_dwordx4 v[196:199], v9, s[10:11] offset:32
	global_load_dwordx4 v[200:203], v9, s[10:11] offset:64
	global_load_dwordx4 v[204:207], v9, s[10:11] offset:96
	s_waitcnt vmcnt(16)
	v_mfma_f32_32x32x16_bf16 v[16:31], v[80:83], v[112:115], 0
	v_mfma_f32_32x32x16_bf16 v[32:47], v[80:83], v[128:131], 0
	v_mfma_f32_32x32x16_bf16 v[48:63], v[96:99], v[112:115], 0
	v_mfma_f32_32x32x16_bf16 v[64:79], v[96:99], v[128:131], 0
	v_mfma_f32_32x32x16_bf16 v[16:31], v[84:87], v[116:119], v[16:31]
	v_mfma_f32_32x32x16_bf16 v[32:47], v[84:87], v[132:135], v[32:47]
	v_mfma_f32_32x32x16_bf16 v[48:63], v[100:103], v[116:119], v[48:63]
	v_mfma_f32_32x32x16_bf16 v[64:79], v[100:103], v[132:135], v[64:79]
	v_mfma_f32_32x32x16_bf16 v[16:31], v[88:91], v[120:123], v[16:31]
	v_mfma_f32_32x32x16_bf16 v[32:47], v[88:91], v[136:139], v[32:47]
	v_mfma_f32_32x32x16_bf16 v[48:63], v[104:107], v[120:123], v[48:63]
	v_mfma_f32_32x32x16_bf16 v[64:79], v[104:107], v[136:139], v[64:79]
	v_mfma_f32_32x32x16_bf16 v[16:31], v[92:95], v[124:127], v[16:31]
	v_mfma_f32_32x32x16_bf16 v[32:47], v[92:95], v[140:143], v[32:47]
	v_mfma_f32_32x32x16_bf16 v[48:63], v[108:111], v[124:127], v[48:63]
	v_mfma_f32_32x32x16_bf16 v[64:79], v[108:111], v[140:143], v[64:79]
	s_waitcnt vmcnt(0)
	v_mfma_f32_32x32x16_bf16 v[16:31], v[144:147], v[176:179], v[16:31]
	v_mfma_f32_32x32x16_bf16 v[32:47], v[144:147], v[192:195], v[32:47]
	v_mfma_f32_32x32x16_bf16 v[48:63], v[160:163], v[176:179], v[48:63]
	v_mfma_f32_32x32x16_bf16 v[64:79], v[160:163], v[192:195], v[64:79]
	v_mfma_f32_32x32x16_bf16 v[16:31], v[148:151], v[180:183], v[16:31]
	v_mfma_f32_32x32x16_bf16 v[32:47], v[148:151], v[196:199], v[32:47]
	v_mfma_f32_32x32x16_bf16 v[48:63], v[164:167], v[180:183], v[48:63]
	v_mfma_f32_32x32x16_bf16 v[64:79], v[164:167], v[196:199], v[64:79]
	v_mfma_f32_32x32x16_bf16 v[16:31], v[152:155], v[184:187], v[16:31]
	v_mfma_f32_32x32x16_bf16 v[32:47], v[152:155], v[200:203], v[32:47]
	v_mfma_f32_32x32x16_bf16 v[48:63], v[168:171], v[184:187], v[48:63]
	v_mfma_f32_32x32x16_bf16 v[64:79], v[168:171], v[200:203], v[64:79]
	v_mfma_f32_32x32x16_bf16 v[16:31], v[156:159], v[188:191], v[16:31]
	v_mfma_f32_32x32x16_bf16 v[32:47], v[156:159], v[204:207], v[32:47]
	v_mfma_f32_32x32x16_bf16 v[48:63], v[172:175], v[188:191], v[48:63]
	v_mfma_f32_32x32x16_bf16 v[64:79], v[172:175], v[204:207], v[64:79]
	s_nop 15
	global_load_dwordx4 v[80:83], v5, s[12:13] offset:0
	global_load_dwordx4 v[84:87], v5, s[12:13] offset:32
	global_load_dwordx4 v[88:91], v5, s[12:13] offset:64
	global_load_dwordx4 v[92:95], v5, s[12:13] offset:96
	global_load_dwordx4 v[96:99], v5, s[14:15] offset:0
	global_load_dwordx4 v[100:103], v5, s[14:15] offset:32
	global_load_dwordx4 v[104:107], v5, s[14:15] offset:64
	global_load_dwordx4 v[108:111], v5, s[14:15] offset:96
	global_load_dwordx4 v[112:115], v5, s[16:17] offset:0
	global_load_dwordx4 v[116:119], v5, s[16:17] offset:32
	global_load_dwordx4 v[120:123], v5, s[16:17] offset:64
	global_load_dwordx4 v[124:127], v5, s[16:17] offset:96
	global_load_dwordx4 v[128:131], v5, s[18:19] offset:0
	global_load_dwordx4 v[132:135], v5, s[18:19] offset:32
	global_load_dwordx4 v[136:139], v5, s[18:19] offset:64
	global_load_dwordx4 v[140:143], v5, s[18:19] offset:96
	global_load_dword v208, v7, s[22:23]
	global_load_dwordx4 v[144:147], v9, s[12:13] offset:0
	global_load_dwordx4 v[148:151], v9, s[12:13] offset:32
	global_load_dwordx4 v[152:155], v9, s[12:13] offset:64
	global_load_dwordx4 v[156:159], v9, s[12:13] offset:96
	global_load_dwordx4 v[160:163], v9, s[14:15] offset:0
	global_load_dwordx4 v[164:167], v9, s[14:15] offset:32
	global_load_dwordx4 v[168:171], v9, s[14:15] offset:64
	global_load_dwordx4 v[172:175], v9, s[14:15] offset:96
	global_load_dwordx4 v[176:179], v9, s[16:17] offset:0
	global_load_dwordx4 v[180:183], v9, s[16:17] offset:32
	global_load_dwordx4 v[184:187], v9, s[16:17] offset:64
	global_load_dwordx4 v[188:191], v9, s[16:17] offset:96
	global_load_dwordx4 v[192:195], v9, s[18:19] offset:0
	global_load_dwordx4 v[196:199], v9, s[18:19] offset:32
	global_load_dwordx4 v[200:203], v9, s[18:19] offset:64
	global_load_dwordx4 v[204:207], v9, s[18:19] offset:96
	global_load_dword v250, v8, s[22:23]
	s_waitcnt vmcnt(17) lgkmcnt(0)
; DI float lo_bf(unsigned u) { return __uint_as_float(u << 16); }
; DI float hi_bf(unsigned u) { return __uint_as_float(u & 0xffff0000u); }
; DI void phase_finalize(int wv, const Params& p, int l, LAS unsigned char* lds) {
;     ...
;             for (int q = 0; q < 8; ++q) { const u32x4 zv = zr[q], yv = yr[q];
; #pragma unroll
;                 for (int e = 0; e < 4; ++e) { z[4 * q + e] = (f32x2){lo_bf(zv[e]), hi_bf(zv[e])}; y[8 * q + 2 * e] += lo_bf(yv[e]); y[8 * q + 2 * e + 1] += hi_bf(yv[e]); } }
;     ...
;         if (valid) {
;             float mean = 0.f;
; #pragma unroll
;             for (int i = 0; i < 64; ++i) mean += y[i];
;             mean *= (1.f / 64);
	s_nop 1
	v_permlane32_swap_b32_e32 v80, v82
	v_permlane32_swap_b32_e32 v81, v83
	v_permlane32_swap_b32_e32 v84, v86
	v_permlane32_swap_b32_e32 v85, v87
	v_permlane32_swap_b32_e32 v88, v90
	v_permlane32_swap_b32_e32 v89, v91
	v_permlane32_swap_b32_e32 v92, v94
	v_permlane32_swap_b32_e32 v93, v95
	v_permlane32_swap_b32_e32 v96, v98
	v_permlane32_swap_b32_e32 v97, v99
	v_permlane32_swap_b32_e32 v100, v102
	v_permlane32_swap_b32_e32 v101, v103
	v_permlane32_swap_b32_e32 v104, v106
	v_permlane32_swap_b32_e32 v105, v107
	v_permlane32_swap_b32_e32 v108, v110
	v_permlane32_swap_b32_e32 v109, v111
	v_permlane32_swap_b32_e32 v112, v114
	v_permlane32_swap_b32_e32 v113, v115
	v_permlane32_swap_b32_e32 v116, v118
	v_permlane32_swap_b32_e32 v117, v119
	v_permlane32_swap_b32_e32 v120, v122
	v_permlane32_swap_b32_e32 v121, v123
	v_permlane32_swap_b32_e32 v124, v126
	v_permlane32_swap_b32_e32 v125, v127
	v_permlane32_swap_b32_e32 v128, v130
	v_permlane32_swap_b32_e32 v129, v131
	v_permlane32_swap_b32_e32 v132, v134
	v_permlane32_swap_b32_e32 v133, v135
	v_permlane32_swap_b32_e32 v136, v138
	v_permlane32_swap_b32_e32 v137, v139
	v_permlane32_swap_b32_e32 v140, v142
	v_permlane32_swap_b32_e32 v141, v143
	v_lshlrev_b32_e32 v209, 16, v80
	v_add_f32_e32 v16, v16, v209
	v_and_b32_e32 v210, 0xffff0000, v80
	v_add_f32_e32 v17, v17, v210
	v_lshlrev_b32_e32 v209, 16, v81
	v_add_f32_e32 v18, v18, v209
	v_and_b32_e32 v210, 0xffff0000, v81
	v_add_f32_e32 v19, v19, v210
	v_lshlrev_b32_e32 v209, 16, v96
	v_add_f32_e32 v16, v16, v209
	v_and_b32_e32 v210, 0xffff0000, v96
	v_add_f32_e32 v17, v17, v210
	v_lshlrev_b32_e32 v209, 16, v97
	v_add_f32_e32 v18, v18, v209
	v_and_b32_e32 v210, 0xffff0000, v97
	v_add_f32_e32 v19, v19, v210
	v_lshlrev_b32_e32 v209, 16, v82
	v_add_f32_e32 v20, v20, v209
	v_and_b32_e32 v210, 0xffff0000, v82
	v_add_f32_e32 v21, v21, v210
	v_lshlrev_b32_e32 v209, 16, v83
	v_add_f32_e32 v22, v22, v209
	v_and_b32_e32 v210, 0xffff0000, v83
	v_add_f32_e32 v23, v23, v210
	v_lshlrev_b32_e32 v209, 16, v98
	v_add_f32_e32 v20, v20, v209
	v_and_b32_e32 v210, 0xffff0000, v98
	v_add_f32_e32 v21, v21, v210
	v_lshlrev_b32_e32 v209, 16, v99
	v_add_f32_e32 v22, v22, v209
	v_and_b32_e32 v210, 0xffff0000, v99
	v_add_f32_e32 v23, v23, v210
	v_lshlrev_b32_e32 v209, 16, v84
	v_add_f32_e32 v24, v24, v209
	v_and_b32_e32 v210, 0xffff0000, v84
	v_add_f32_e32 v25, v25, v210
	v_lshlrev_b32_e32 v209, 16, v85
	v_add_f32_e32 v26, v26, v209
	v_and_b32_e32 v210, 0xffff0000, v85
	v_add_f32_e32 v27, v27, v210
	v_lshlrev_b32_e32 v209, 16, v100
	v_add_f32_e32 v24, v24, v209
	v_and_b32_e32 v210, 0xffff0000, v100
	v_add_f32_e32 v25, v25, v210
	v_lshlrev_b32_e32 v209, 16, v101
	v_add_f32_e32 v26, v26, v209
	v_and_b32_e32 v210, 0xffff0000, v101
	v_add_f32_e32 v27, v27, v210
	v_lshlrev_b32_e32 v209, 16, v86
	v_add_f32_e32 v28, v28, v209
	v_and_b32_e32 v210, 0xffff0000, v86
	v_add_f32_e32 v29, v29, v210
	v_lshlrev_b32_e32 v209, 16, v87
	v_add_f32_e32 v30, v30, v209
	v_and_b32_e32 v210, 0xffff0000, v87
	v_add_f32_e32 v31, v31, v210
	v_lshlrev_b32_e32 v209, 16, v102
	v_add_f32_e32 v28, v28, v209
	v_and_b32_e32 v210, 0xffff0000, v102
	v_add_f32_e32 v29, v29, v210
	v_lshlrev_b32_e32 v209, 16, v103
	v_add_f32_e32 v30, v30, v209
	v_and_b32_e32 v210, 0xffff0000, v103
	v_add_f32_e32 v31, v31, v210
	v_lshlrev_b32_e32 v209, 16, v88
	v_add_f32_e32 v48, v48, v209
	v_and_b32_e32 v210, 0xffff0000, v88
	v_add_f32_e32 v49, v49, v210
	v_lshlrev_b32_e32 v209, 16, v89
	v_add_f32_e32 v50, v50, v209
	v_and_b32_e32 v210, 0xffff0000, v89
	v_add_f32_e32 v51, v51, v210
	v_lshlrev_b32_e32 v209, 16, v104
	v_add_f32_e32 v48, v48, v209
	v_and_b32_e32 v210, 0xffff0000, v104
	v_add_f32_e32 v49, v49, v210
	v_lshlrev_b32_e32 v209, 16, v105
	v_add_f32_e32 v50, v50, v209
	v_and_b32_e32 v210, 0xffff0000, v105
	v_add_f32_e32 v51, v51, v210
	v_lshlrev_b32_e32 v209, 16, v90
	v_add_f32_e32 v52, v52, v209
	v_and_b32_e32 v210, 0xffff0000, v90
	v_add_f32_e32 v53, v53, v210
	v_lshlrev_b32_e32 v209, 16, v91
	v_add_f32_e32 v54, v54, v209
	v_and_b32_e32 v210, 0xffff0000, v91
	v_add_f32_e32 v55, v55, v210
	v_lshlrev_b32_e32 v209, 16, v106
	v_add_f32_e32 v52, v52, v209
	v_and_b32_e32 v210, 0xffff0000, v106
	v_add_f32_e32 v53, v53, v210
	v_lshlrev_b32_e32 v209, 16, v107
	v_add_f32_e32 v54, v54, v209
	v_and_b32_e32 v210, 0xffff0000, v107
	v_add_f32_e32 v55, v55, v210
	v_lshlrev_b32_e32 v209, 16, v92
	v_add_f32_e32 v56, v56, v209
	v_and_b32_e32 v210, 0xffff0000, v92
	v_add_f32_e32 v57, v57, v210
	v_lshlrev_b32_e32 v209, 16, v93
	v_add_f32_e32 v58, v58, v209
	v_and_b32_e32 v210, 0xffff0000, v93
	v_add_f32_e32 v59, v59, v210
	v_lshlrev_b32_e32 v209, 16, v108
	v_add_f32_e32 v56, v56, v209
	v_and_b32_e32 v210, 0xffff0000, v108
	v_add_f32_e32 v57, v57, v210
	v_lshlrev_b32_e32 v209, 16, v109
	v_add_f32_e32 v58, v58, v209
	v_and_b32_e32 v210, 0xffff0000, v109
	v_add_f32_e32 v59, v59, v210
	v_lshlrev_b32_e32 v209, 16, v94
	v_add_f32_e32 v60, v60, v209
	v_and_b32_e32 v210, 0xffff0000, v94
	v_add_f32_e32 v61, v61, v210
	v_lshlrev_b32_e32 v209, 16, v95
	v_add_f32_e32 v62, v62, v209
	v_and_b32_e32 v210, 0xffff0000, v95
	v_add_f32_e32 v63, v63, v210
	v_lshlrev_b32_e32 v209, 16, v110
	v_add_f32_e32 v60, v60, v209
	v_and_b32_e32 v210, 0xffff0000, v110
	v_add_f32_e32 v61, v61, v210
	v_lshlrev_b32_e32 v209, 16, v111
	v_add_f32_e32 v62, v62, v209
	v_and_b32_e32 v210, 0xffff0000, v111
	v_add_f32_e32 v63, v63, v210
	v_add_f32_e32 v211, v16, v17
	v_add_f32_e32 v212, v18, v19
	v_add_f32_e32 v211, v211, v20
	v_add_f32_e32 v212, v212, v21
	v_add_f32_e32 v211, v211, v22
	v_add_f32_e32 v212, v212, v23
	v_add_f32_e32 v211, v211, v24
	v_add_f32_e32 v212, v212, v25
	v_add_f32_e32 v211, v211, v26
	v_add_f32_e32 v212, v212, v27
	v_add_f32_e32 v211, v211, v28
	v_add_f32_e32 v212, v212, v29
	v_add_f32_e32 v211, v211, v30
	v_add_f32_e32 v212, v212, v31
	v_add_f32_e32 v211, v211, v48
	v_add_f32_e32 v212, v212, v49
	v_add_f32_e32 v211, v211, v50
	v_add_f32_e32 v212, v212, v51
	v_add_f32_e32 v211, v211, v52
	v_add_f32_e32 v212, v212, v53
	v_add_f32_e32 v211, v211, v54
	v_add_f32_e32 v212, v212, v55
	v_add_f32_e32 v211, v211, v56
	v_add_f32_e32 v212, v212, v57
	v_add_f32_e32 v211, v211, v58
	v_add_f32_e32 v212, v212, v59
	v_add_f32_e32 v211, v211, v60
	v_add_f32_e32 v212, v212, v61
	v_add_f32_e32 v211, v211, v62
	v_add_f32_e32 v212, v212, v63
	v_add_f32_e32 v211, v211, v212
	ds_bpermute_b32 v212, v15, v211
	s_waitcnt lgkmcnt(0)
; DI unsigned pack2(float lo, float hi) { f32x2 v = {lo, hi}; bf16v2 r = __builtin_convertvector(v, bf16v2); return __builtin_bit_cast(unsigned, r); }
; DI float lo_bf(unsigned u) { return __uint_as_float(u << 16); }
; DI float hi_bf(unsigned u) { return __uint_as_float(u & 0xffff0000u); }
; DI void phase_finalize(int wv, const Params& p, int l, LAS unsigned char* lds) {
;     ...
;             float var = 0.f;
; #pragma unroll
;             for (int i = 0; i < 64; ++i) { const float d = y[i] - mean; var += d * d; }
;             const float rs = __builtin_amdgcn_rsqf(var * (1.f / 64) + 64e-5f);
;             const float bon = BON[row * 4 + hd];
;             u32x4 vr[8], gr[8];
; #pragma unroll
;             for (int q = 0; q < 8; ++q) { vr[q] = *(const u32x4*)(VV + row * 256 + hd * 64 + 8 * q); gr[q] = *(const u32x4*)(G + row * 256 + hd * 64 + 8 * q); }
;             __builtin_amdgcn_sched_barrier(0);
; #pragma unroll
;             for (int q = 0; q < 8; ++q) {
;                 const u32x4 vv = vr[q], gv = gr[q];
;                 const f32x4 g0 = *(const f32x4*)(lng + 8 * q), g1 = *(const f32x4*)(lng + 8 * q + 4), b0 = *(const f32x4*)(lnb + 8 * q), b1 = *(const f32x4*)(lnb + 8 * q + 4);
;                 float o8[8];
; #pragma unroll
;                 for (int e = 0; e < 8; ++e) {
;                     const float gn = (y[8 * q + e] - mean) * rs * (e < 4 ? g0[e] : g1[e - 4]) + (e < 4 ? b0[e] : b1[e - 4]);
;                     const float ve = (e & 1) ? hi_bf(vv[e >> 1]) : lo_bf(vv[e >> 1]), ge = (e & 1) ? hi_bf(gv[e >> 1]) : lo_bf(gv[e >> 1]);
;                     o8[e] = (gn + bon * ve) * ge;
;                 }
;                 u32x4 pk = {pack2(o8[0], o8[1]), pack2(o8[2], o8[3]), pack2(o8[4], o8[5]), pack2(o8[6], o8[7])};
;                 *(u32x4*)(MIX + row * 1024 + hd * 64 + 8 * q) = pk;
	v_add_f32_e32 v211, v211, v212
	v_mul_f32_e32 v211, 0x3c800000, v211
	v_sub_f32_e32 v16, v16, v211
	v_sub_f32_e32 v17, v17, v211
	v_mul_f32_e32 v213, v16, v16
	v_mul_f32_e32 v214, v17, v17
	v_sub_f32_e32 v18, v18, v211
	v_sub_f32_e32 v19, v19, v211
	v_fmac_f32_e32 v213, v18, v18
	v_fmac_f32_e32 v214, v19, v19
	v_sub_f32_e32 v20, v20, v211
	v_sub_f32_e32 v21, v21, v211
	v_fmac_f32_e32 v213, v20, v20
	v_fmac_f32_e32 v214, v21, v21
	v_sub_f32_e32 v22, v22, v211
	v_sub_f32_e32 v23, v23, v211
	v_fmac_f32_e32 v213, v22, v22
	v_fmac_f32_e32 v214, v23, v23
	v_sub_f32_e32 v24, v24, v211
	v_sub_f32_e32 v25, v25, v211
	v_fmac_f32_e32 v213, v24, v24
	v_fmac_f32_e32 v214, v25, v25
	v_sub_f32_e32 v26, v26, v211
	v_sub_f32_e32 v27, v27, v211
	v_fmac_f32_e32 v213, v26, v26
	v_fmac_f32_e32 v214, v27, v27
	v_sub_f32_e32 v28, v28, v211
	v_sub_f32_e32 v29, v29, v211
	v_fmac_f32_e32 v213, v28, v28
	v_fmac_f32_e32 v214, v29, v29
	v_sub_f32_e32 v30, v30, v211
	v_sub_f32_e32 v31, v31, v211
	v_fmac_f32_e32 v213, v30, v30
	v_fmac_f32_e32 v214, v31, v31
	v_sub_f32_e32 v48, v48, v211
	v_sub_f32_e32 v49, v49, v211
	v_fmac_f32_e32 v213, v48, v48
	v_fmac_f32_e32 v214, v49, v49
	v_sub_f32_e32 v50, v50, v211
	v_sub_f32_e32 v51, v51, v211
	v_fmac_f32_e32 v213, v50, v50
	v_fmac_f32_e32 v214, v51, v51
	v_sub_f32_e32 v52, v52, v211
	v_sub_f32_e32 v53, v53, v211
	v_fmac_f32_e32 v213, v52, v52
	v_fmac_f32_e32 v214, v53, v53
	v_sub_f32_e32 v54, v54, v211
	v_sub_f32_e32 v55, v55, v211
	v_fmac_f32_e32 v213, v54, v54
	v_fmac_f32_e32 v214, v55, v55
	v_sub_f32_e32 v56, v56, v211
	v_sub_f32_e32 v57, v57, v211
	v_fmac_f32_e32 v213, v56, v56
	v_fmac_f32_e32 v214, v57, v57
	v_sub_f32_e32 v58, v58, v211
	v_sub_f32_e32 v59, v59, v211
	v_fmac_f32_e32 v213, v58, v58
	v_fmac_f32_e32 v214, v59, v59
	v_sub_f32_e32 v60, v60, v211
	v_sub_f32_e32 v61, v61, v211
	v_fmac_f32_e32 v213, v60, v60
	v_fmac_f32_e32 v214, v61, v61
	v_sub_f32_e32 v62, v62, v211
	v_sub_f32_e32 v63, v63, v211
	v_fmac_f32_e32 v213, v62, v62
	v_fmac_f32_e32 v214, v63, v63
	v_add_f32_e32 v213, v213, v214
	ds_bpermute_b32 v214, v15, v213
	s_waitcnt lgkmcnt(0)
	v_add_f32_e32 v213, v213, v214
	v_mul_f32_e32 v213, 0x3c800000, v213
	v_add_f32_e32 v213, 0x3a27c5ac, v213
	v_rsq_f32_e32 v213, v213
	s_nop 0
	ds_read_b128 v[234:237], v232 offset:0
	ds_read_b128 v[238:241], v232 offset:256
	ds_read_b128 v[242:245], v232 offset:32
	ds_read_b128 v[246:249], v232 offset:288
	s_waitcnt lgkmcnt(2)
	v_mul_f32_e32 v16, v16, v213
	v_fma_f32 v16, v16, v234, v238
	v_lshlrev_b32_e32 v209, 16, v112
	v_lshlrev_b32_e32 v210, 16, v128
	v_fma_f32 v16, v208, v209, v16
	v_mul_f32_e32 v16, v16, v210
	v_mul_f32_e32 v17, v17, v213
	v_fma_f32 v17, v17, v235, v239
	v_and_b32_e32 v209, 0xffff0000, v112
	v_and_b32_e32 v210, 0xffff0000, v128
	v_fma_f32 v17, v208, v209, v17
	v_mul_f32_e32 v17, v17, v210
	v_mul_f32_e32 v18, v18, v213
	v_fma_f32 v18, v18, v236, v240
	v_lshlrev_b32_e32 v209, 16, v113
	v_lshlrev_b32_e32 v210, 16, v129
	v_fma_f32 v18, v208, v209, v18
	v_mul_f32_e32 v18, v18, v210
	v_mul_f32_e32 v19, v19, v213
	v_fma_f32 v19, v19, v237, v241
	v_and_b32_e32 v209, 0xffff0000, v113
	v_and_b32_e32 v210, 0xffff0000, v129
	v_fma_f32 v19, v208, v209, v19
	v_mul_f32_e32 v19, v19, v210
	v_cvt_pk_bf16_f32 v216, v16, v17
	v_cvt_pk_bf16_f32 v217, v18, v19
	ds_read_b128 v[234:237], v232 offset:64
	ds_read_b128 v[238:241], v232 offset:320
	s_waitcnt lgkmcnt(2)
	v_mul_f32_e32 v20, v20, v213
	v_fma_f32 v20, v20, v242, v246
	v_lshlrev_b32_e32 v209, 16, v114
	v_lshlrev_b32_e32 v210, 16, v130
	v_fma_f32 v20, v208, v209, v20
	v_mul_f32_e32 v20, v20, v210
	v_mul_f32_e32 v21, v21, v213
	v_fma_f32 v21, v21, v243, v247
	v_and_b32_e32 v209, 0xffff0000, v114
	v_and_b32_e32 v210, 0xffff0000, v130
	v_fma_f32 v21, v208, v209, v21
	v_mul_f32_e32 v21, v21, v210
	v_mul_f32_e32 v22, v22, v213
	v_fma_f32 v22, v22, v244, v248
	v_lshlrev_b32_e32 v209, 16, v115
	v_lshlrev_b32_e32 v210, 16, v131
	v_fma_f32 v22, v208, v209, v22
	v_mul_f32_e32 v22, v22, v210
	v_mul_f32_e32 v23, v23, v213
	v_fma_f32 v23, v23, v245, v249
	v_and_b32_e32 v209, 0xffff0000, v115
	v_and_b32_e32 v210, 0xffff0000, v131
	v_fma_f32 v23, v208, v209, v23
	v_mul_f32_e32 v23, v23, v210
	v_cvt_pk_bf16_f32 v218, v20, v21
	v_cvt_pk_bf16_f32 v219, v22, v23
	ds_read_b128 v[242:245], v232 offset:96
	ds_read_b128 v[246:249], v232 offset:352
	s_waitcnt lgkmcnt(2)
	v_mul_f32_e32 v24, v24, v213
	v_fma_f32 v24, v24, v234, v238
	v_lshlrev_b32_e32 v209, 16, v116
	v_lshlrev_b32_e32 v210, 16, v132
	v_fma_f32 v24, v208, v209, v24
	v_mul_f32_e32 v24, v24, v210
	v_mul_f32_e32 v25, v25, v213
	v_fma_f32 v25, v25, v235, v239
	v_and_b32_e32 v209, 0xffff0000, v116
	v_and_b32_e32 v210, 0xffff0000, v132
	v_fma_f32 v25, v208, v209, v25
	v_mul_f32_e32 v25, v25, v210
	v_mul_f32_e32 v26, v26, v213
	v_fma_f32 v26, v26, v236, v240
	v_lshlrev_b32_e32 v209, 16, v117
	v_lshlrev_b32_e32 v210, 16, v133
	v_fma_f32 v26, v208, v209, v26
	v_mul_f32_e32 v26, v26, v210
	v_mul_f32_e32 v27, v27, v213
	v_fma_f32 v27, v27, v237, v241
	v_and_b32_e32 v209, 0xffff0000, v117
	v_and_b32_e32 v210, 0xffff0000, v133
	v_fma_f32 v27, v208, v209, v27
	v_mul_f32_e32 v27, v27, v210
	v_cvt_pk_bf16_f32 v220, v24, v25
	v_cvt_pk_bf16_f32 v221, v26, v27
	ds_read_b128 v[234:237], v232 offset:128
	ds_read_b128 v[238:241], v232 offset:384
	s_waitcnt lgkmcnt(2)
; DI unsigned pack2(float lo, float hi) { f32x2 v = {lo, hi}; bf16v2 r = __builtin_convertvector(v, bf16v2); return __builtin_bit_cast(unsigned, r); }
; DI float lo_bf(unsigned u) { return __uint_as_float(u << 16); }
; DI float hi_bf(unsigned u) { return __uint_as_float(u & 0xffff0000u); }
; DI void phase_finalize(int wv, const Params& p, int l, LAS unsigned char* lds) {
;     ...
;             for (int q = 0; q < 8; ++q) {
;                 const u32x4 vv = vr[q], gv = gr[q];
;                 const f32x4 g0 = *(const f32x4*)(lng + 8 * q), g1 = *(const f32x4*)(lng + 8 * q + 4), b0 = *(const f32x4*)(lnb + 8 * q), b1 = *(const f32x4*)(lnb + 8 * q + 4);
;                 float o8[8];
; #pragma unroll
;                 for (int e = 0; e < 8; ++e) {
;                     const float gn = (y[8 * q + e] - mean) * rs * (e < 4 ? g0[e] : g1[e - 4]) + (e < 4 ? b0[e] : b1[e - 4]);
;                     const float ve = (e & 1) ? hi_bf(vv[e >> 1]) : lo_bf(vv[e >> 1]), ge = (e & 1) ? hi_bf(gv[e >> 1]) : lo_bf(gv[e >> 1]);
;                     o8[e] = (gn + bon * ve) * ge;
;                 }
;                 u32x4 pk = {pack2(o8[0], o8[1]), pack2(o8[2], o8[3]), pack2(o8[4], o8[5]), pack2(o8[6], o8[7])};
;                 *(u32x4*)(MIX + row * 1024 + hd * 64 + 8 * q) = pk;
;             }
	v_mul_f32_e32 v28, v28, v213
	v_fma_f32 v28, v28, v242, v246
	v_lshlrev_b32_e32 v209, 16, v118
	v_lshlrev_b32_e32 v210, 16, v134
	v_fma_f32 v28, v208, v209, v28
	v_mul_f32_e32 v28, v28, v210
	v_mul_f32_e32 v29, v29, v213
	v_fma_f32 v29, v29, v243, v247
	v_and_b32_e32 v209, 0xffff0000, v118
	v_and_b32_e32 v210, 0xffff0000, v134
	v_fma_f32 v29, v208, v209, v29
	v_mul_f32_e32 v29, v29, v210
	v_mul_f32_e32 v30, v30, v213
	v_fma_f32 v30, v30, v244, v248
	v_lshlrev_b32_e32 v209, 16, v119
	v_lshlrev_b32_e32 v210, 16, v135
	v_fma_f32 v30, v208, v209, v30
	v_mul_f32_e32 v30, v30, v210
	v_mul_f32_e32 v31, v31, v213
	v_fma_f32 v31, v31, v245, v249
	v_and_b32_e32 v209, 0xffff0000, v119
	v_and_b32_e32 v210, 0xffff0000, v135
	v_fma_f32 v31, v208, v209, v31
	v_mul_f32_e32 v31, v31, v210
	v_cvt_pk_bf16_f32 v222, v28, v29
	v_cvt_pk_bf16_f32 v223, v30, v31
	ds_read_b128 v[242:245], v232 offset:160
	ds_read_b128 v[246:249], v232 offset:416
	s_waitcnt lgkmcnt(2)
	v_mul_f32_e32 v48, v48, v213
	v_fma_f32 v48, v48, v234, v238
	v_lshlrev_b32_e32 v209, 16, v120
	v_lshlrev_b32_e32 v210, 16, v136
	v_fma_f32 v48, v208, v209, v48
	v_mul_f32_e32 v48, v48, v210
	v_mul_f32_e32 v49, v49, v213
	v_fma_f32 v49, v49, v235, v239
	v_and_b32_e32 v209, 0xffff0000, v120
	v_and_b32_e32 v210, 0xffff0000, v136
	v_fma_f32 v49, v208, v209, v49
	v_mul_f32_e32 v49, v49, v210
	v_mul_f32_e32 v50, v50, v213
	v_fma_f32 v50, v50, v236, v240
	v_lshlrev_b32_e32 v209, 16, v121
	v_lshlrev_b32_e32 v210, 16, v137
	v_fma_f32 v50, v208, v209, v50
	v_mul_f32_e32 v50, v50, v210
	v_mul_f32_e32 v51, v51, v213
	v_fma_f32 v51, v51, v237, v241
	v_and_b32_e32 v209, 0xffff0000, v121
	v_and_b32_e32 v210, 0xffff0000, v137
	v_fma_f32 v51, v208, v209, v51
	v_mul_f32_e32 v51, v51, v210
	v_cvt_pk_bf16_f32 v224, v48, v49
	v_cvt_pk_bf16_f32 v225, v50, v51
	ds_read_b128 v[234:237], v232 offset:192
	ds_read_b128 v[238:241], v232 offset:448
	s_waitcnt lgkmcnt(2)
	v_mul_f32_e32 v52, v52, v213
	v_fma_f32 v52, v52, v242, v246
	v_lshlrev_b32_e32 v209, 16, v122
	v_lshlrev_b32_e32 v210, 16, v138
	v_fma_f32 v52, v208, v209, v52
	v_mul_f32_e32 v52, v52, v210
	v_mul_f32_e32 v53, v53, v213
	v_fma_f32 v53, v53, v243, v247
	v_and_b32_e32 v209, 0xffff0000, v122
	v_and_b32_e32 v210, 0xffff0000, v138
	v_fma_f32 v53, v208, v209, v53
	v_mul_f32_e32 v53, v53, v210
	v_mul_f32_e32 v54, v54, v213
	v_fma_f32 v54, v54, v244, v248
	v_lshlrev_b32_e32 v209, 16, v123
	v_lshlrev_b32_e32 v210, 16, v139
	v_fma_f32 v54, v208, v209, v54
	v_mul_f32_e32 v54, v54, v210
	v_mul_f32_e32 v55, v55, v213
	v_fma_f32 v55, v55, v245, v249
	v_and_b32_e32 v209, 0xffff0000, v123
	v_and_b32_e32 v210, 0xffff0000, v139
	v_fma_f32 v55, v208, v209, v55
	v_mul_f32_e32 v55, v55, v210
	v_cvt_pk_bf16_f32 v226, v52, v53
	v_cvt_pk_bf16_f32 v227, v54, v55
	ds_read_b128 v[242:245], v232 offset:224
	ds_read_b128 v[246:249], v232 offset:480
	s_waitcnt lgkmcnt(2)
	v_mul_f32_e32 v56, v56, v213
	v_fma_f32 v56, v56, v234, v238
	v_lshlrev_b32_e32 v209, 16, v124
	v_lshlrev_b32_e32 v210, 16, v140
	v_fma_f32 v56, v208, v209, v56
	v_mul_f32_e32 v56, v56, v210
	v_mul_f32_e32 v57, v57, v213
	v_fma_f32 v57, v57, v235, v239
	v_and_b32_e32 v209, 0xffff0000, v124
	v_and_b32_e32 v210, 0xffff0000, v140
	v_fma_f32 v57, v208, v209, v57
	v_mul_f32_e32 v57, v57, v210
	v_mul_f32_e32 v58, v58, v213
	v_fma_f32 v58, v58, v236, v240
	v_lshlrev_b32_e32 v209, 16, v125
	v_lshlrev_b32_e32 v210, 16, v141
	v_fma_f32 v58, v208, v209, v58
	v_mul_f32_e32 v58, v58, v210
	v_mul_f32_e32 v59, v59, v213
	v_fma_f32 v59, v59, v237, v241
	v_and_b32_e32 v209, 0xffff0000, v125
	v_and_b32_e32 v210, 0xffff0000, v141
	v_fma_f32 v59, v208, v209, v59
	v_mul_f32_e32 v59, v59, v210
	v_cvt_pk_bf16_f32 v228, v56, v57
	v_cvt_pk_bf16_f32 v229, v58, v59
	s_waitcnt lgkmcnt(0)
	v_mul_f32_e32 v60, v60, v213
	v_fma_f32 v60, v60, v242, v246
	v_lshlrev_b32_e32 v209, 16, v126
	v_lshlrev_b32_e32 v210, 16, v142
	v_fma_f32 v60, v208, v209, v60
	v_mul_f32_e32 v60, v60, v210
	v_mul_f32_e32 v61, v61, v213
	v_fma_f32 v61, v61, v243, v247
	v_and_b32_e32 v209, 0xffff0000, v126
	v_and_b32_e32 v210, 0xffff0000, v142
	v_fma_f32 v61, v208, v209, v61
	v_mul_f32_e32 v61, v61, v210
	v_mul_f32_e32 v62, v62, v213
	v_fma_f32 v62, v62, v244, v248
	v_lshlrev_b32_e32 v209, 16, v127
	v_lshlrev_b32_e32 v210, 16, v143
	v_fma_f32 v62, v208, v209, v62
	v_mul_f32_e32 v62, v62, v210
	v_mul_f32_e32 v63, v63, v213
	v_fma_f32 v63, v63, v245, v249
	v_and_b32_e32 v209, 0xffff0000, v127
	v_and_b32_e32 v210, 0xffff0000, v143
	v_fma_f32 v63, v208, v209, v63
	v_mul_f32_e32 v63, v63, v210
	v_cvt_pk_bf16_f32 v230, v60, v61
	v_cvt_pk_bf16_f32 v231, v62, v63
	s_nop 1
	v_permlane32_swap_b32_e32 v216, v218
	v_permlane32_swap_b32_e32 v217, v219
	v_permlane32_swap_b32_e32 v220, v222
	v_permlane32_swap_b32_e32 v221, v223
	v_permlane32_swap_b32_e32 v224, v226
	v_permlane32_swap_b32_e32 v225, v227
	v_permlane32_swap_b32_e32 v228, v230
	v_permlane32_swap_b32_e32 v229, v231
	s_and_saveexec_b64 s[50:51], s[36:37]
	s_cbranch_execz .Lfina_skipst0
	global_store_dwordx4 v12, v[216:219], s[20:21] offset:0
	global_store_dwordx4 v12, v[220:223], s[20:21] offset:32
	global_store_dwordx4 v12, v[224:227], s[20:21] offset:64
	global_store_dwordx4 v12, v[228:231], s[20:21] offset:96
; DI float lo_bf(unsigned u) { return __uint_as_float(u << 16); }
; DI float hi_bf(unsigned u) { return __uint_as_float(u & 0xffff0000u); }
; DI void phase_finalize(int wv, const Params& p, int l, LAS unsigned char* lds) {
;     ...
;             for (int q = 0; q < 8; ++q) { const u32x4 zv = zr[q], yv = yr[q];
; #pragma unroll
;                 for (int e = 0; e < 4; ++e) { z[4 * q + e] = (f32x2){lo_bf(zv[e]), hi_bf(zv[e])}; y[8 * q + 2 * e] += lo_bf(yv[e]); y[8 * q + 2 * e + 1] += hi_bf(yv[e]); } }
;     ...
;         if (valid) {
;             float mean = 0.f;
; #pragma unroll
;             for (int i = 0; i < 64; ++i) mean += y[i];
;             mean *= (1.f / 64);
.Lfina_skipst0:
	s_mov_b64 exec, s[50:51]
	s_waitcnt vmcnt(0) lgkmcnt(0)
	s_nop 1
	v_permlane32_swap_b32_e32 v144, v146
	v_permlane32_swap_b32_e32 v145, v147
	v_permlane32_swap_b32_e32 v148, v150
	v_permlane32_swap_b32_e32 v149, v151
	v_permlane32_swap_b32_e32 v152, v154
	v_permlane32_swap_b32_e32 v153, v155
	v_permlane32_swap_b32_e32 v156, v158
	v_permlane32_swap_b32_e32 v157, v159
	v_permlane32_swap_b32_e32 v160, v162
	v_permlane32_swap_b32_e32 v161, v163
	v_permlane32_swap_b32_e32 v164, v166
	v_permlane32_swap_b32_e32 v165, v167
	v_permlane32_swap_b32_e32 v168, v170
	v_permlane32_swap_b32_e32 v169, v171
	v_permlane32_swap_b32_e32 v172, v174
	v_permlane32_swap_b32_e32 v173, v175
	v_permlane32_swap_b32_e32 v176, v178
	v_permlane32_swap_b32_e32 v177, v179
	v_permlane32_swap_b32_e32 v180, v182
	v_permlane32_swap_b32_e32 v181, v183
	v_permlane32_swap_b32_e32 v184, v186
	v_permlane32_swap_b32_e32 v185, v187
	v_permlane32_swap_b32_e32 v188, v190
	v_permlane32_swap_b32_e32 v189, v191
	v_permlane32_swap_b32_e32 v192, v194
	v_permlane32_swap_b32_e32 v193, v195
	v_permlane32_swap_b32_e32 v196, v198
	v_permlane32_swap_b32_e32 v197, v199
	v_permlane32_swap_b32_e32 v200, v202
	v_permlane32_swap_b32_e32 v201, v203
	v_permlane32_swap_b32_e32 v204, v206
	v_permlane32_swap_b32_e32 v205, v207
	v_lshlrev_b32_e32 v209, 16, v144
	v_add_f32_e32 v32, v32, v209
	v_and_b32_e32 v210, 0xffff0000, v144
	v_add_f32_e32 v33, v33, v210
	v_lshlrev_b32_e32 v209, 16, v145
	v_add_f32_e32 v34, v34, v209
	v_and_b32_e32 v210, 0xffff0000, v145
	v_add_f32_e32 v35, v35, v210
	v_lshlrev_b32_e32 v209, 16, v160
	v_add_f32_e32 v32, v32, v209
	v_and_b32_e32 v210, 0xffff0000, v160
	v_add_f32_e32 v33, v33, v210
	v_lshlrev_b32_e32 v209, 16, v161
	v_add_f32_e32 v34, v34, v209
	v_and_b32_e32 v210, 0xffff0000, v161
	v_add_f32_e32 v35, v35, v210
	v_lshlrev_b32_e32 v209, 16, v146
	v_add_f32_e32 v36, v36, v209
	v_and_b32_e32 v210, 0xffff0000, v146
	v_add_f32_e32 v37, v37, v210
	v_lshlrev_b32_e32 v209, 16, v147
	v_add_f32_e32 v38, v38, v209
	v_and_b32_e32 v210, 0xffff0000, v147
	v_add_f32_e32 v39, v39, v210
	v_lshlrev_b32_e32 v209, 16, v162
	v_add_f32_e32 v36, v36, v209
	v_and_b32_e32 v210, 0xffff0000, v162
	v_add_f32_e32 v37, v37, v210
	v_lshlrev_b32_e32 v209, 16, v163
	v_add_f32_e32 v38, v38, v209
	v_and_b32_e32 v210, 0xffff0000, v163
	v_add_f32_e32 v39, v39, v210
	v_lshlrev_b32_e32 v209, 16, v148
	v_add_f32_e32 v40, v40, v209
	v_and_b32_e32 v210, 0xffff0000, v148
	v_add_f32_e32 v41, v41, v210
	v_lshlrev_b32_e32 v209, 16, v149
	v_add_f32_e32 v42, v42, v209
	v_and_b32_e32 v210, 0xffff0000, v149
	v_add_f32_e32 v43, v43, v210
	v_lshlrev_b32_e32 v209, 16, v164
	v_add_f32_e32 v40, v40, v209
	v_and_b32_e32 v210, 0xffff0000, v164
	v_add_f32_e32 v41, v41, v210
	v_lshlrev_b32_e32 v209, 16, v165
	v_add_f32_e32 v42, v42, v209
	v_and_b32_e32 v210, 0xffff0000, v165
	v_add_f32_e32 v43, v43, v210
	v_lshlrev_b32_e32 v209, 16, v150
	v_add_f32_e32 v44, v44, v209
	v_and_b32_e32 v210, 0xffff0000, v150
	v_add_f32_e32 v45, v45, v210
	v_lshlrev_b32_e32 v209, 16, v151
	v_add_f32_e32 v46, v46, v209
	v_and_b32_e32 v210, 0xffff0000, v151
	v_add_f32_e32 v47, v47, v210
	v_lshlrev_b32_e32 v209, 16, v166
	v_add_f32_e32 v44, v44, v209
	v_and_b32_e32 v210, 0xffff0000, v166
	v_add_f32_e32 v45, v45, v210
	v_lshlrev_b32_e32 v209, 16, v167
	v_add_f32_e32 v46, v46, v209
	v_and_b32_e32 v210, 0xffff0000, v167
	v_add_f32_e32 v47, v47, v210
	v_lshlrev_b32_e32 v209, 16, v152
	v_add_f32_e32 v64, v64, v209
	v_and_b32_e32 v210, 0xffff0000, v152
	v_add_f32_e32 v65, v65, v210
	v_lshlrev_b32_e32 v209, 16, v153
	v_add_f32_e32 v66, v66, v209
	v_and_b32_e32 v210, 0xffff0000, v153
	v_add_f32_e32 v67, v67, v210
	v_lshlrev_b32_e32 v209, 16, v168
	v_add_f32_e32 v64, v64, v209
	v_and_b32_e32 v210, 0xffff0000, v168
	v_add_f32_e32 v65, v65, v210
	v_lshlrev_b32_e32 v209, 16, v169
	v_add_f32_e32 v66, v66, v209
	v_and_b32_e32 v210, 0xffff0000, v169
	v_add_f32_e32 v67, v67, v210
	v_lshlrev_b32_e32 v209, 16, v154
	v_add_f32_e32 v68, v68, v209
	v_and_b32_e32 v210, 0xffff0000, v154
	v_add_f32_e32 v69, v69, v210
	v_lshlrev_b32_e32 v209, 16, v155
	v_add_f32_e32 v70, v70, v209
	v_and_b32_e32 v210, 0xffff0000, v155
	v_add_f32_e32 v71, v71, v210
	v_lshlrev_b32_e32 v209, 16, v170
	v_add_f32_e32 v68, v68, v209
	v_and_b32_e32 v210, 0xffff0000, v170
	v_add_f32_e32 v69, v69, v210
	v_lshlrev_b32_e32 v209, 16, v171
	v_add_f32_e32 v70, v70, v209
	v_and_b32_e32 v210, 0xffff0000, v171
	v_add_f32_e32 v71, v71, v210
	v_lshlrev_b32_e32 v209, 16, v156
	v_add_f32_e32 v72, v72, v209
	v_and_b32_e32 v210, 0xffff0000, v156
	v_add_f32_e32 v73, v73, v210
	v_lshlrev_b32_e32 v209, 16, v157
	v_add_f32_e32 v74, v74, v209
	v_and_b32_e32 v210, 0xffff0000, v157
	v_add_f32_e32 v75, v75, v210
	v_lshlrev_b32_e32 v209, 16, v172
	v_add_f32_e32 v72, v72, v209
	v_and_b32_e32 v210, 0xffff0000, v172
	v_add_f32_e32 v73, v73, v210
	v_lshlrev_b32_e32 v209, 16, v173
	v_add_f32_e32 v74, v74, v209
	v_and_b32_e32 v210, 0xffff0000, v173
	v_add_f32_e32 v75, v75, v210
	v_lshlrev_b32_e32 v209, 16, v158
	v_add_f32_e32 v76, v76, v209
	v_and_b32_e32 v210, 0xffff0000, v158
	v_add_f32_e32 v77, v77, v210
	v_lshlrev_b32_e32 v209, 16, v159
	v_add_f32_e32 v78, v78, v209
	v_and_b32_e32 v210, 0xffff0000, v159
	v_add_f32_e32 v79, v79, v210
	v_lshlrev_b32_e32 v209, 16, v174
	v_add_f32_e32 v76, v76, v209
	v_and_b32_e32 v210, 0xffff0000, v174
	v_add_f32_e32 v77, v77, v210
	v_lshlrev_b32_e32 v209, 16, v175
	v_add_f32_e32 v78, v78, v209
	v_and_b32_e32 v210, 0xffff0000, v175
	v_add_f32_e32 v79, v79, v210
	v_add_f32_e32 v211, v32, v33
	v_add_f32_e32 v212, v34, v35
	v_add_f32_e32 v211, v211, v36
	v_add_f32_e32 v212, v212, v37
	v_add_f32_e32 v211, v211, v38
	v_add_f32_e32 v212, v212, v39
	v_add_f32_e32 v211, v211, v40
	v_add_f32_e32 v212, v212, v41
	v_add_f32_e32 v211, v211, v42
	v_add_f32_e32 v212, v212, v43
	v_add_f32_e32 v211, v211, v44
	v_add_f32_e32 v212, v212, v45
	v_add_f32_e32 v211, v211, v46
	v_add_f32_e32 v212, v212, v47
	v_add_f32_e32 v211, v211, v64
	v_add_f32_e32 v212, v212, v65
	v_add_f32_e32 v211, v211, v66
	v_add_f32_e32 v212, v212, v67
	v_add_f32_e32 v211, v211, v68
	v_add_f32_e32 v212, v212, v69
	v_add_f32_e32 v211, v211, v70
	v_add_f32_e32 v212, v212, v71
	v_add_f32_e32 v211, v211, v72
	v_add_f32_e32 v212, v212, v73
	v_add_f32_e32 v211, v211, v74
	v_add_f32_e32 v212, v212, v75
	v_add_f32_e32 v211, v211, v76
	v_add_f32_e32 v212, v212, v77
	v_add_f32_e32 v211, v211, v78
	v_add_f32_e32 v212, v212, v79
	v_add_f32_e32 v211, v211, v212
	ds_bpermute_b32 v212, v15, v211
	s_waitcnt lgkmcnt(0)
; DI unsigned pack2(float lo, float hi) { f32x2 v = {lo, hi}; bf16v2 r = __builtin_convertvector(v, bf16v2); return __builtin_bit_cast(unsigned, r); }
; DI float lo_bf(unsigned u) { return __uint_as_float(u << 16); }
; DI float hi_bf(unsigned u) { return __uint_as_float(u & 0xffff0000u); }
; DI void phase_finalize(int wv, const Params& p, int l, LAS unsigned char* lds) {
;     ...
;             float var = 0.f;
; #pragma unroll
;             for (int i = 0; i < 64; ++i) { const float d = y[i] - mean; var += d * d; }
;             const float rs = __builtin_amdgcn_rsqf(var * (1.f / 64) + 64e-5f);
;             const float bon = BON[row * 4 + hd];
;             u32x4 vr[8], gr[8];
; #pragma unroll
;             for (int q = 0; q < 8; ++q) { vr[q] = *(const u32x4*)(VV + row * 256 + hd * 64 + 8 * q); gr[q] = *(const u32x4*)(G + row * 256 + hd * 64 + 8 * q); }
;             __builtin_amdgcn_sched_barrier(0);
; #pragma unroll
;             for (int q = 0; q < 8; ++q) {
;                 const u32x4 vv = vr[q], gv = gr[q];
;                 const f32x4 g0 = *(const f32x4*)(lng + 8 * q), g1 = *(const f32x4*)(lng + 8 * q + 4), b0 = *(const f32x4*)(lnb + 8 * q), b1 = *(const f32x4*)(lnb + 8 * q + 4);
;                 float o8[8];
; #pragma unroll
;                 for (int e = 0; e < 8; ++e) {
;                     const float gn = (y[8 * q + e] - mean) * rs * (e < 4 ? g0[e] : g1[e - 4]) + (e < 4 ? b0[e] : b1[e - 4]);
;                     const float ve = (e & 1) ? hi_bf(vv[e >> 1]) : lo_bf(vv[e >> 1]), ge = (e & 1) ? hi_bf(gv[e >> 1]) : lo_bf(gv[e >> 1]);
;                     o8[e] = (gn + bon * ve) * ge;
;                 }
;                 u32x4 pk = {pack2(o8[0], o8[1]), pack2(o8[2], o8[3]), pack2(o8[4], o8[5]), pack2(o8[6], o8[7])};
;                 *(u32x4*)(MIX + row * 1024 + hd * 64 + 8 * q) = pk;
	v_add_f32_e32 v211, v211, v212
	v_mul_f32_e32 v211, 0x3c800000, v211
	v_sub_f32_e32 v32, v32, v211
	v_sub_f32_e32 v33, v33, v211
	v_mul_f32_e32 v213, v32, v32
	v_mul_f32_e32 v214, v33, v33
	v_sub_f32_e32 v34, v34, v211
	v_sub_f32_e32 v35, v35, v211
	v_fmac_f32_e32 v213, v34, v34
	v_fmac_f32_e32 v214, v35, v35
	v_sub_f32_e32 v36, v36, v211
	v_sub_f32_e32 v37, v37, v211
	v_fmac_f32_e32 v213, v36, v36
	v_fmac_f32_e32 v214, v37, v37
	v_sub_f32_e32 v38, v38, v211
	v_sub_f32_e32 v39, v39, v211
	v_fmac_f32_e32 v213, v38, v38
	v_fmac_f32_e32 v214, v39, v39
	v_sub_f32_e32 v40, v40, v211
	v_sub_f32_e32 v41, v41, v211
	v_fmac_f32_e32 v213, v40, v40
	v_fmac_f32_e32 v214, v41, v41
	v_sub_f32_e32 v42, v42, v211
	v_sub_f32_e32 v43, v43, v211
	v_fmac_f32_e32 v213, v42, v42
	v_fmac_f32_e32 v214, v43, v43
	v_sub_f32_e32 v44, v44, v211
	v_sub_f32_e32 v45, v45, v211
	v_fmac_f32_e32 v213, v44, v44
	v_fmac_f32_e32 v214, v45, v45
	v_sub_f32_e32 v46, v46, v211
	v_sub_f32_e32 v47, v47, v211
	v_fmac_f32_e32 v213, v46, v46
	v_fmac_f32_e32 v214, v47, v47
	v_sub_f32_e32 v64, v64, v211
	v_sub_f32_e32 v65, v65, v211
	v_fmac_f32_e32 v213, v64, v64
	v_fmac_f32_e32 v214, v65, v65
	v_sub_f32_e32 v66, v66, v211
	v_sub_f32_e32 v67, v67, v211
	v_fmac_f32_e32 v213, v66, v66
	v_fmac_f32_e32 v214, v67, v67
	v_sub_f32_e32 v68, v68, v211
	v_sub_f32_e32 v69, v69, v211
	v_fmac_f32_e32 v213, v68, v68
	v_fmac_f32_e32 v214, v69, v69
	v_sub_f32_e32 v70, v70, v211
	v_sub_f32_e32 v71, v71, v211
	v_fmac_f32_e32 v213, v70, v70
	v_fmac_f32_e32 v214, v71, v71
	v_sub_f32_e32 v72, v72, v211
	v_sub_f32_e32 v73, v73, v211
	v_fmac_f32_e32 v213, v72, v72
	v_fmac_f32_e32 v214, v73, v73
	v_sub_f32_e32 v74, v74, v211
	v_sub_f32_e32 v75, v75, v211
	v_fmac_f32_e32 v213, v74, v74
	v_fmac_f32_e32 v214, v75, v75
	v_sub_f32_e32 v76, v76, v211
	v_sub_f32_e32 v77, v77, v211
	v_fmac_f32_e32 v213, v76, v76
	v_fmac_f32_e32 v214, v77, v77
	v_sub_f32_e32 v78, v78, v211
	v_sub_f32_e32 v79, v79, v211
	v_fmac_f32_e32 v213, v78, v78
	v_fmac_f32_e32 v214, v79, v79
	v_add_f32_e32 v213, v213, v214
	ds_bpermute_b32 v214, v15, v213
	s_waitcnt lgkmcnt(0)
	v_add_f32_e32 v213, v213, v214
	v_mul_f32_e32 v213, 0x3c800000, v213
	v_add_f32_e32 v213, 0x3a27c5ac, v213
	v_rsq_f32_e32 v213, v213
	s_nop 0
	ds_read_b128 v[234:237], v232 offset:0
	ds_read_b128 v[238:241], v232 offset:256
	ds_read_b128 v[242:245], v232 offset:32
	ds_read_b128 v[246:249], v232 offset:288
	s_waitcnt lgkmcnt(2)
	v_mul_f32_e32 v32, v32, v213
	v_fma_f32 v32, v32, v234, v238
	v_lshlrev_b32_e32 v209, 16, v176
	v_lshlrev_b32_e32 v210, 16, v192
	v_fma_f32 v32, v250, v209, v32
	v_mul_f32_e32 v32, v32, v210
	v_mul_f32_e32 v33, v33, v213
	v_fma_f32 v33, v33, v235, v239
	v_and_b32_e32 v209, 0xffff0000, v176
	v_and_b32_e32 v210, 0xffff0000, v192
	v_fma_f32 v33, v250, v209, v33
	v_mul_f32_e32 v33, v33, v210
	v_mul_f32_e32 v34, v34, v213
	v_fma_f32 v34, v34, v236, v240
	v_lshlrev_b32_e32 v209, 16, v177
	v_lshlrev_b32_e32 v210, 16, v193
	v_fma_f32 v34, v250, v209, v34
	v_mul_f32_e32 v34, v34, v210
	v_mul_f32_e32 v35, v35, v213
	v_fma_f32 v35, v35, v237, v241
	v_and_b32_e32 v209, 0xffff0000, v177
	v_and_b32_e32 v210, 0xffff0000, v193
	v_fma_f32 v35, v250, v209, v35
	v_mul_f32_e32 v35, v35, v210
	v_cvt_pk_bf16_f32 v216, v32, v33
	v_cvt_pk_bf16_f32 v217, v34, v35
	ds_read_b128 v[234:237], v232 offset:64
	ds_read_b128 v[238:241], v232 offset:320
	s_waitcnt lgkmcnt(2)
	v_mul_f32_e32 v36, v36, v213
	v_fma_f32 v36, v36, v242, v246
	v_lshlrev_b32_e32 v209, 16, v178
	v_lshlrev_b32_e32 v210, 16, v194
	v_fma_f32 v36, v250, v209, v36
	v_mul_f32_e32 v36, v36, v210
	v_mul_f32_e32 v37, v37, v213
	v_fma_f32 v37, v37, v243, v247
	v_and_b32_e32 v209, 0xffff0000, v178
	v_and_b32_e32 v210, 0xffff0000, v194
	v_fma_f32 v37, v250, v209, v37
	v_mul_f32_e32 v37, v37, v210
	v_mul_f32_e32 v38, v38, v213
	v_fma_f32 v38, v38, v244, v248
	v_lshlrev_b32_e32 v209, 16, v179
	v_lshlrev_b32_e32 v210, 16, v195
	v_fma_f32 v38, v250, v209, v38
	v_mul_f32_e32 v38, v38, v210
	v_mul_f32_e32 v39, v39, v213
	v_fma_f32 v39, v39, v245, v249
	v_and_b32_e32 v209, 0xffff0000, v179
	v_and_b32_e32 v210, 0xffff0000, v195
	v_fma_f32 v39, v250, v209, v39
	v_mul_f32_e32 v39, v39, v210
	v_cvt_pk_bf16_f32 v218, v36, v37
	v_cvt_pk_bf16_f32 v219, v38, v39
	ds_read_b128 v[242:245], v232 offset:96
	ds_read_b128 v[246:249], v232 offset:352
	s_waitcnt lgkmcnt(2)
	v_mul_f32_e32 v40, v40, v213
	v_fma_f32 v40, v40, v234, v238
	v_lshlrev_b32_e32 v209, 16, v180
	v_lshlrev_b32_e32 v210, 16, v196
	v_fma_f32 v40, v250, v209, v40
	v_mul_f32_e32 v40, v40, v210
	v_mul_f32_e32 v41, v41, v213
	v_fma_f32 v41, v41, v235, v239
	v_and_b32_e32 v209, 0xffff0000, v180
	v_and_b32_e32 v210, 0xffff0000, v196
	v_fma_f32 v41, v250, v209, v41
	v_mul_f32_e32 v41, v41, v210
	v_mul_f32_e32 v42, v42, v213
	v_fma_f32 v42, v42, v236, v240
	v_lshlrev_b32_e32 v209, 16, v181
	v_lshlrev_b32_e32 v210, 16, v197
	v_fma_f32 v42, v250, v209, v42
	v_mul_f32_e32 v42, v42, v210
	v_mul_f32_e32 v43, v43, v213
	v_fma_f32 v43, v43, v237, v241
	v_and_b32_e32 v209, 0xffff0000, v181
	v_and_b32_e32 v210, 0xffff0000, v197
	v_fma_f32 v43, v250, v209, v43
	v_mul_f32_e32 v43, v43, v210
	v_cvt_pk_bf16_f32 v220, v40, v41
	v_cvt_pk_bf16_f32 v221, v42, v43
	ds_read_b128 v[234:237], v232 offset:128
	ds_read_b128 v[238:241], v232 offset:384
	s_waitcnt lgkmcnt(2)
; DI unsigned pack2(float lo, float hi) { f32x2 v = {lo, hi}; bf16v2 r = __builtin_convertvector(v, bf16v2); return __builtin_bit_cast(unsigned, r); }
; DI float lo_bf(unsigned u) { return __uint_as_float(u << 16); }
; DI float hi_bf(unsigned u) { return __uint_as_float(u & 0xffff0000u); }
; DI void phase_finalize(int wv, const Params& p, int l, LAS unsigned char* lds) {
;     ...
;             for (int q = 0; q < 8; ++q) {
;                 const u32x4 vv = vr[q], gv = gr[q];
;                 const f32x4 g0 = *(const f32x4*)(lng + 8 * q), g1 = *(const f32x4*)(lng + 8 * q + 4), b0 = *(const f32x4*)(lnb + 8 * q), b1 = *(const f32x4*)(lnb + 8 * q + 4);
;                 float o8[8];
; #pragma unroll
;                 for (int e = 0; e < 8; ++e) {
;                     const float gn = (y[8 * q + e] - mean) * rs * (e < 4 ? g0[e] : g1[e - 4]) + (e < 4 ? b0[e] : b1[e - 4]);
;                     const float ve = (e & 1) ? hi_bf(vv[e >> 1]) : lo_bf(vv[e >> 1]), ge = (e & 1) ? hi_bf(gv[e >> 1]) : lo_bf(gv[e >> 1]);
;                     o8[e] = (gn + bon * ve) * ge;
;                 }
;                 u32x4 pk = {pack2(o8[0], o8[1]), pack2(o8[2], o8[3]), pack2(o8[4], o8[5]), pack2(o8[6], o8[7])};
;                 *(u32x4*)(MIX + row * 1024 + hd * 64 + 8 * q) = pk;
;             }
	v_mul_f32_e32 v44, v44, v213
	v_fma_f32 v44, v44, v242, v246
	v_lshlrev_b32_e32 v209, 16, v182
	v_lshlrev_b32_e32 v210, 16, v198
	v_fma_f32 v44, v250, v209, v44
	v_mul_f32_e32 v44, v44, v210
	v_mul_f32_e32 v45, v45, v213
	v_fma_f32 v45, v45, v243, v247
	v_and_b32_e32 v209, 0xffff0000, v182
	v_and_b32_e32 v210, 0xffff0000, v198
	v_fma_f32 v45, v250, v209, v45
	v_mul_f32_e32 v45, v45, v210
	v_mul_f32_e32 v46, v46, v213
	v_fma_f32 v46, v46, v244, v248
	v_lshlrev_b32_e32 v209, 16, v183
	v_lshlrev_b32_e32 v210, 16, v199
	v_fma_f32 v46, v250, v209, v46
	v_mul_f32_e32 v46, v46, v210
	v_mul_f32_e32 v47, v47, v213
	v_fma_f32 v47, v47, v245, v249
	v_and_b32_e32 v209, 0xffff0000, v183
	v_and_b32_e32 v210, 0xffff0000, v199
	v_fma_f32 v47, v250, v209, v47
	v_mul_f32_e32 v47, v47, v210
	v_cvt_pk_bf16_f32 v222, v44, v45
	v_cvt_pk_bf16_f32 v223, v46, v47
	ds_read_b128 v[242:245], v232 offset:160
	ds_read_b128 v[246:249], v232 offset:416
	s_waitcnt lgkmcnt(2)
	v_mul_f32_e32 v64, v64, v213
	v_fma_f32 v64, v64, v234, v238
	v_lshlrev_b32_e32 v209, 16, v184
	v_lshlrev_b32_e32 v210, 16, v200
	v_fma_f32 v64, v250, v209, v64
	v_mul_f32_e32 v64, v64, v210
	v_mul_f32_e32 v65, v65, v213
	v_fma_f32 v65, v65, v235, v239
	v_and_b32_e32 v209, 0xffff0000, v184
	v_and_b32_e32 v210, 0xffff0000, v200
	v_fma_f32 v65, v250, v209, v65
	v_mul_f32_e32 v65, v65, v210
	v_mul_f32_e32 v66, v66, v213
	v_fma_f32 v66, v66, v236, v240
	v_lshlrev_b32_e32 v209, 16, v185
	v_lshlrev_b32_e32 v210, 16, v201
	v_fma_f32 v66, v250, v209, v66
	v_mul_f32_e32 v66, v66, v210
	v_mul_f32_e32 v67, v67, v213
	v_fma_f32 v67, v67, v237, v241
	v_and_b32_e32 v209, 0xffff0000, v185
	v_and_b32_e32 v210, 0xffff0000, v201
	v_fma_f32 v67, v250, v209, v67
	v_mul_f32_e32 v67, v67, v210
	v_cvt_pk_bf16_f32 v224, v64, v65
	v_cvt_pk_bf16_f32 v225, v66, v67
	ds_read_b128 v[234:237], v232 offset:192
	ds_read_b128 v[238:241], v232 offset:448
	s_waitcnt lgkmcnt(2)
	v_mul_f32_e32 v68, v68, v213
	v_fma_f32 v68, v68, v242, v246
	v_lshlrev_b32_e32 v209, 16, v186
	v_lshlrev_b32_e32 v210, 16, v202
	v_fma_f32 v68, v250, v209, v68
	v_mul_f32_e32 v68, v68, v210
	v_mul_f32_e32 v69, v69, v213
	v_fma_f32 v69, v69, v243, v247
	v_and_b32_e32 v209, 0xffff0000, v186
	v_and_b32_e32 v210, 0xffff0000, v202
	v_fma_f32 v69, v250, v209, v69
	v_mul_f32_e32 v69, v69, v210
	v_mul_f32_e32 v70, v70, v213
	v_fma_f32 v70, v70, v244, v248
	v_lshlrev_b32_e32 v209, 16, v187
	v_lshlrev_b32_e32 v210, 16, v203
	v_fma_f32 v70, v250, v209, v70
	v_mul_f32_e32 v70, v70, v210
	v_mul_f32_e32 v71, v71, v213
	v_fma_f32 v71, v71, v245, v249
	v_and_b32_e32 v209, 0xffff0000, v187
	v_and_b32_e32 v210, 0xffff0000, v203
	v_fma_f32 v71, v250, v209, v71
	v_mul_f32_e32 v71, v71, v210
	v_cvt_pk_bf16_f32 v226, v68, v69
	v_cvt_pk_bf16_f32 v227, v70, v71
	ds_read_b128 v[242:245], v232 offset:224
	ds_read_b128 v[246:249], v232 offset:480
	s_waitcnt lgkmcnt(2)
	v_mul_f32_e32 v72, v72, v213
	v_fma_f32 v72, v72, v234, v238
	v_lshlrev_b32_e32 v209, 16, v188
	v_lshlrev_b32_e32 v210, 16, v204
	v_fma_f32 v72, v250, v209, v72
	v_mul_f32_e32 v72, v72, v210
	v_mul_f32_e32 v73, v73, v213
	v_fma_f32 v73, v73, v235, v239
	v_and_b32_e32 v209, 0xffff0000, v188
	v_and_b32_e32 v210, 0xffff0000, v204
	v_fma_f32 v73, v250, v209, v73
	v_mul_f32_e32 v73, v73, v210
	v_mul_f32_e32 v74, v74, v213
	v_fma_f32 v74, v74, v236, v240
	v_lshlrev_b32_e32 v209, 16, v189
	v_lshlrev_b32_e32 v210, 16, v205
	v_fma_f32 v74, v250, v209, v74
	v_mul_f32_e32 v74, v74, v210
	v_mul_f32_e32 v75, v75, v213
	v_fma_f32 v75, v75, v237, v241
	v_and_b32_e32 v209, 0xffff0000, v189
	v_and_b32_e32 v210, 0xffff0000, v205
	v_fma_f32 v75, v250, v209, v75
	v_mul_f32_e32 v75, v75, v210
	v_cvt_pk_bf16_f32 v228, v72, v73
	v_cvt_pk_bf16_f32 v229, v74, v75
	s_waitcnt lgkmcnt(0)
	v_mul_f32_e32 v76, v76, v213
	v_fma_f32 v76, v76, v242, v246
	v_lshlrev_b32_e32 v209, 16, v190
	v_lshlrev_b32_e32 v210, 16, v206
	v_fma_f32 v76, v250, v209, v76
	v_mul_f32_e32 v76, v76, v210
	v_mul_f32_e32 v77, v77, v213
	v_fma_f32 v77, v77, v243, v247
	v_and_b32_e32 v209, 0xffff0000, v190
	v_and_b32_e32 v210, 0xffff0000, v206
	v_fma_f32 v77, v250, v209, v77
	v_mul_f32_e32 v77, v77, v210
	v_mul_f32_e32 v78, v78, v213
	v_fma_f32 v78, v78, v244, v248
	v_lshlrev_b32_e32 v209, 16, v191
	v_lshlrev_b32_e32 v210, 16, v207
	v_fma_f32 v78, v250, v209, v78
	v_mul_f32_e32 v78, v78, v210
	v_mul_f32_e32 v79, v79, v213
	v_fma_f32 v79, v79, v245, v249
	v_and_b32_e32 v209, 0xffff0000, v191
	v_and_b32_e32 v210, 0xffff0000, v207
	v_fma_f32 v79, v250, v209, v79
	v_mul_f32_e32 v79, v79, v210
	v_cvt_pk_bf16_f32 v230, v76, v77
	v_cvt_pk_bf16_f32 v231, v78, v79
	s_nop 1
	v_permlane32_swap_b32_e32 v216, v218
	v_permlane32_swap_b32_e32 v217, v219
	v_permlane32_swap_b32_e32 v220, v222
	v_permlane32_swap_b32_e32 v221, v223
	v_permlane32_swap_b32_e32 v224, v226
	v_permlane32_swap_b32_e32 v225, v227
	v_permlane32_swap_b32_e32 v228, v230
	v_permlane32_swap_b32_e32 v229, v231
	s_and_saveexec_b64 s[50:51], s[38:39]
	s_cbranch_execz .Lfina_skipst1
	global_store_dwordx4 v0, v[216:219], s[20:21] offset:0
	global_store_dwordx4 v0, v[220:223], s[20:21] offset:32
	global_store_dwordx4 v0, v[224:227], s[20:21] offset:64
	global_store_dwordx4 v0, v[228:231], s[20:21] offset:96

; #define LAS __attribute__((address_space(3)))
; DI void phase_finalize(int wv, const Params& p, int l, LAS unsigned char* lds) {
;     unsigned char* ob = (unsigned char*)p.out;
;     const bf16_t* YL = (const bf16_t*)(ob + O_YL); const bf16_t* ZZ = (const bf16_t*)(p.ws + R_Z); const bf16_t* UU = (const bf16_t*)(ob + O_U);
;     const float* BON = (const float*)(ob + O_BON);
;     const bf16_t* VV = (const bf16_t*)(p.ws + R_VV); const bf16_t* G = (const bf16_t*)(p.ws + R_G); bf16_t* MIX = (bf16_t*)(p.ws + R_MIX);
;     const int tid = tid_(wv), lane = tid & 63, w = tid >> 6, hd = w >> 1, half = w & 1;
;     LAS float* Ssm = (LAS float*)lds;
;     const float* lng = p.in[19] + (size_t)l * 256 + hd * 64; const float* lnb = p.in[20] + (size_t)l * 256 + hd * 64;
;     ...
;                 const f32x4 g0 = *(const f32x4*)(lng + 8 * q), g1 = *(const f32x4*)(lng + 8 * q + 4), b0 = *(const f32x4*)(lnb + 8 * q), b1 = *(const f32x4*)(lnb + 8 * q + 4);
.LBB0_2932:
	s_or_b64 exec, exec, s[4:5]
	s_waitcnt lgkmcnt(0)
	v_mov_b32_e32 v0, v254
	s_andn2_b64 vcc, exec, s[36:37]
	s_barrier
	v_writelane_b32 v255, s4, 17
	v_writelane_b32 v255, s5, 18
	v_writelane_b32 v255, s6, 19
	v_writelane_b32 v255, s7, 20
	v_writelane_b32 v255, s8, 21
	v_writelane_b32 v255, s9, 22
	v_writelane_b32 v255, s10, 23
	v_writelane_b32 v255, s11, 24
	v_writelane_b32 v255, s12, 25
	v_writelane_b32 v255, s13, 26
	v_writelane_b32 v255, s14, 27
	v_writelane_b32 v255, s15, 28
	v_writelane_b32 v255, s16, 29
	v_writelane_b32 v255, s17, 30
	v_writelane_b32 v255, s18, 31
	v_writelane_b32 v255, s19, 32
	v_writelane_b32 v255, s20, 33
	v_writelane_b32 v255, s21, 34
	v_writelane_b32 v255, s22, 35
	v_writelane_b32 v255, s23, 36
	v_writelane_b32 v255, s24, 37
	v_writelane_b32 v255, s25, 38
	v_writelane_b32 v255, s26, 39
	v_writelane_b32 v255, s27, 40
	v_writelane_b32 v255, s28, 41
	v_writelane_b32 v255, s29, 42
	v_writelane_b32 v255, s30, 43
	v_writelane_b32 v255, s31, 44
	v_writelane_b32 v255, s36, 45
	v_writelane_b32 v255, s37, 46
	v_writelane_b32 v255, s38, 47
	v_writelane_b32 v255, s39, 48
	v_writelane_b32 v255, s40, 49
	v_writelane_b32 v255, s41, 50
	v_writelane_b32 v255, s42, 51
	v_writelane_b32 v255, s43, 52
	v_writelane_b32 v255, s44, 53
	v_writelane_b32 v255, s45, 54
	v_writelane_b32 v255, s46, 55
	v_writelane_b32 v255, s47, 56
	v_writelane_b32 v255, s48, 57
	v_writelane_b32 v255, s49, 58
	v_writelane_b32 v255, s50, 59
	v_writelane_b32 v255, s51, 60
	s_load_dwordx2 s[40:41], s[0:1], 0x120
	s_load_dwordx4 s[24:27], s[0:1], 0x98
	s_lshr_b32 s29, s33, 7
	s_bfe_u32 s30, s33, 0x10006
	s_lshl_b32 s31, s29, 7
	v_and_b32_e32 v1, 31, v254
	v_lshrrev_b32_e32 v2, 5, v254
	v_lshlrev_b32_e32 v13, 4, v2
	v_lshlrev_b32_e32 v14, 3, v2
	v_lshl_add_u32 v3, v1, 7, v13
	v_add_u32_e32 v4, 0x1000, v3
	v_add_u32_e32 v6, 32, v1
	v_xor_b32_e32 v15, 32, v254
	v_lshlrev_b32_e32 v15, 2, v15
	s_waitcnt lgkmcnt(0)
	s_add_u32 s8, s34, 0x3a228000
	s_addc_u32 s9, s35, 0
	s_add_u32 s8, s8, s31
	s_addc_u32 s9, s9, 0
	s_add_u32 s10, s8, 0x2860000
	s_addc_u32 s11, s9, 0
	s_add_u32 s12, s40, 0x64f0000
	s_addc_u32 s13, s41, 0
	s_add_u32 s12, s12, s31
	s_addc_u32 s13, s13, 0
	s_add_u32 s14, s12, 0x2860000
	s_addc_u32 s15, s13, 0
	s_add_u32 s16, s34, 0x379c8000
	s_addc_u32 s17, s35, 0
	s_add_u32 s16, s16, s31
	s_addc_u32 s17, s17, 0
	s_add_u32 s18, s34, 0x236c8000
	s_addc_u32 s19, s35, 0
	s_add_u32 s18, s18, s31
	s_addc_u32 s19, s19, 0
	s_add_u32 s20, s34, 0x19548000
	s_addc_u32 s21, s35, 0
	s_add_u32 s20, s20, s31
	s_addc_u32 s21, s21, 0
	s_add_u32 s22, s40, 0x10b13000
	s_addc_u32 s23, s41, 0
	s_lshl_b32 s42, s29, 2
	s_add_u32 s22, s22, s42
	s_addc_u32 s23, s23, 0
	s_lshl_b32 s42, s29, 8
	s_add_u32 s42, s42, 0x400
	s_add_u32 s24, s24, s42
	s_addc_u32 s25, s25, 0
	s_add_u32 s26, s26, s42
	s_addc_u32 s27, s27, 0
	s_add_u32 s48, s40, 0xb5b0000
	s_addc_u32 s49, s41, 0
	v_lshlrev_b32_e32 v232, 4, v254
	v_min_u32_e32 v232, 0xf0, v232
	global_load_dwordx4 v[144:147], v232, s[24:25]
	global_load_dwordx4 v[148:151], v232, s[26:27]
	s_lshl_b32 s42, s33, 4
	v_lshlrev_b32_e32 v233, 4, v254
	v_add_u32_e32 v233, s42, v233
	s_waitcnt vmcnt(0)
	s_mov_b64 s[50:51], exec
	s_mov_b64 exec, 0xffff
	ds_write_b128 v233, v[144:147]
	ds_write_b128 v233, v[148:151] offset:256
	s_mov_b64 exec, s[50:51]
	v_add_u32_e32 v232, s42, v13
	s_waitcnt lgkmcnt(0)
	s_mov_b32 s28, s2
